# attn->G6 becomes a producer-count wait (8 attention workgroups per query-block pair), G7->G8 a 4-workgroup barrier; the XCD-wide conditions they replace are checked one seam later where they are alrea
# speedup vs baseline: 1.0060x; 1.0060x over previous
.LBB0_164:
	s_waitcnt vmcnt(0)
	v_readfirstlane_b32 s0, v194
	s_cmp_gt_u32 s0, 63
	s_waitcnt vmcnt(0)
	s_barrier
	s_cbranch_scc1 .LBB0_218
	v_mbcnt_lo_u32_b32 v0, -1, 0
	v_mbcnt_hi_u32_b32 v0, -1, v0
	s_nop 0
	v_cmp_eq_u32_e32 vcc, 0, v0
	s_and_saveexec_b64 s[0:1], vcc
	s_cbranch_execz .LBB0_217
	v_mov_b32_e32 v0, 0x23ff0
	s_waitcnt vmcnt(0) lgkmcnt(0)
	ds_read_b128 v[0:3], v0
	s_waitcnt lgkmcnt(0)
	v_readfirstlane_b32 s3, v2
	s_nop 0
	s_cmp_eq_u32 s3, 0
	s_cbranch_scc1 .Lfb_slow_0
	v_readfirstlane_b32 s8, v0
	s_cmp_eq_u32 s8, 32
	s_cbranch_scc0 .Lfb_xcd_0
	buffer_inv sc1
	s_getreg_b32 s3, hwreg(HW_REG_XCC_ID, 0, 4)
	s_and_b32 s3, s3, 7
	s_lshl_b32 s3, s3, 8
	s_add_u32 s3, s3, 0x3600
	s_add_u32 s4, s92, 0x510000
	s_addc_u32 s5, s93, 0
	v_mov_b32_e32 v7, 1
	s_bfe_u32 s8, s2, 0x20006
	s_lshl_b32 s8, s8, 2
	s_add_u32 s8, s8, s3
	s_add_u32 s8, s8, 0xe0
	v_mov_b32_e32 v6, s8
	global_atomic_add v6, v7, s[4:5]
	s_bfe_u32 s8, s2, 0x20006
	s_lshl_b32 s8, s8, 2
	s_add_u32 s8, s8, s3
	s_add_u32 s8, s8, 0xe0
	v_mov_b32_e32 v6, s8
	v_mov_b32_e32 v5, 8
	s_mov_b32 s8, 0
	s_branch .Lfb_spin_0

.LBB0_308:
	s_waitcnt vmcnt(0)
	v_readfirstlane_b32 s4, v194
	s_cmp_gt_u32 s4, 63
	v_readlane_b32 s77, v242, 9
	v_readlane_b32 s78, v241, 13
	v_readlane_b32 s40, v241, 12
	v_readlane_b32 s41, v241, 4
	s_barrier
	s_cbranch_scc1 .LBB0_362
	v_mbcnt_lo_u32_b32 v0, -1, 0
	v_mbcnt_hi_u32_b32 v0, -1, v0
	s_nop 0
	v_cmp_eq_u32_e32 vcc, 0, v0
	s_and_saveexec_b64 s[6:7], vcc
	s_cbranch_execz .LBB0_361
	v_mov_b32_e32 v0, 0x23ff0
	s_waitcnt vmcnt(0) lgkmcnt(0)
	ds_read_b128 v[0:3], v0
	s_waitcnt lgkmcnt(0)
	v_readfirstlane_b32 s8, v2
	s_nop 0
	s_cmp_eq_u32 s8, 0
	s_cbranch_scc1 .Lfb_slow_1
	v_readfirstlane_b32 s9, v0
	s_cmp_eq_u32 s9, 32
	s_cbranch_scc0 .Lfb_xcd_1
	buffer_inv sc1
	s_getreg_b32 s8, hwreg(HW_REG_XCC_ID, 0, 4)
	s_and_b32 s8, s8, 7
	s_lshl_b32 s8, s8, 8
	s_add_u32 s8, s8, 0x3600
	s_add_u32 s4, s92, 0x510000
	s_addc_u32 s5, s93, 0
	v_mov_b32_e32 v7, 1
	s_bfe_u32 s9, s2, 0x20006
	s_lshl_b32 s9, s9, 2
	s_add_u32 s9, s9, s8
	s_add_u32 s9, s9, 0xe0
	v_mov_b32_e32 v6, s9
	global_atomic_add v6, v7, s[4:5]
	s_bfe_u32 s9, s2, 0x20006
	s_lshl_b32 s9, s9, 2
	s_add_u32 s9, s9, s8
	s_add_u32 s9, s9, 0xe0
	v_mov_b32_e32 v6, s9
	v_mov_b32_e32 v5, 16
	s_mov_b32 s9, 0
	s_branch .Lfb_spin_1

.LBB0_689:
	s_waitcnt vmcnt(0)
	v_readfirstlane_b32 s3, v194
	s_cmp_gt_u32 s3, 63
	s_waitcnt lgkmcnt(0)
	s_barrier
	s_cbranch_scc1 .LBB0_743
	v_mbcnt_lo_u32_b32 v0, -1, 0
	v_mbcnt_hi_u32_b32 v0, -1, v0
	s_nop 0
	v_cmp_eq_u32_e32 vcc, 0, v0
	s_and_saveexec_b64 s[6:7], vcc
	s_cbranch_execz .LBB0_742
	v_mov_b32_e32 v20, 0x23ff0
	s_waitcnt vmcnt(0) lgkmcnt(0)
	ds_read_b128 v[20:23], v20
	s_waitcnt lgkmcnt(0)
	v_readfirstlane_b32 s3, v22
	s_nop 0
	s_cmp_eq_u32 s3, 0
	s_cbranch_scc1 .Lfb_slow_2
	v_readfirstlane_b32 s8, v20
	s_cmp_eq_u32 s8, 32
	s_cbranch_scc0 .Lfb_xcd_2
	buffer_inv sc1
	s_getreg_b32 s3, hwreg(HW_REG_XCC_ID, 0, 4)
	s_and_b32 s3, s3, 7
	s_lshl_b32 s3, s3, 8
	s_add_u32 s3, s3, 0x3600
	s_add_u32 s4, s92, 0x510000
	s_addc_u32 s5, s93, 0
	v_mov_b32_e32 v27, 1
	s_bfe_u32 s8, s2, 0x30003
	s_lshl_b32 s8, s8, 2
	s_add_u32 s8, s8, s3
	s_add_u32 s8, s8, 0xc0
	v_mov_b32_e32 v26, s8
	global_atomic_add v26, v27, s[4:5]
	s_bfe_u32 s8, s2, 0x30003
	s_lshl_b32 s8, s8, 2
	s_add_u32 s8, s8, s3
	s_add_u32 s8, s8, 0xc0
	v_mov_b32_e32 v26, s8
	v_mov_b32_e32 v25, 4
	s_mov_b32 s8, 0
	s_branch .Lfb_spin_2

.LBB0_772:
	s_waitcnt vmcnt(0)
	v_readfirstlane_b32 s0, v194
	s_cmp_gt_u32 s0, 63
	s_waitcnt vmcnt(0)
	s_barrier
	s_cbranch_scc1 .LBB0_826
	v_mbcnt_lo_u32_b32 v0, -1, 0
	v_mbcnt_hi_u32_b32 v0, -1, v0
	s_nop 0
	v_cmp_eq_u32_e32 vcc, 0, v0
	s_and_saveexec_b64 s[0:1], vcc
	s_cbranch_execz .LBB0_825
	v_mov_b32_e32 v20, 0x23ff0
	s_waitcnt vmcnt(0) lgkmcnt(0)
	ds_read_b128 v[20:23], v20
	s_waitcnt lgkmcnt(0)
	v_readfirstlane_b32 s3, v22
	s_nop 0
	s_cmp_eq_u32 s3, 0
	s_cbranch_scc1 .Lfb_slow_3
	v_readfirstlane_b32 s8, v20
	s_cmp_eq_u32 s8, 32
	s_cbranch_scc0 .Lfb_xcd_3
	buffer_inv sc1
	s_getreg_b32 s3, hwreg(HW_REG_XCC_ID, 0, 4)
	s_and_b32 s3, s3, 7
	s_lshl_b32 s3, s3, 8
	s_add_u32 s3, s3, 0x3600
	s_add_u32 s4, s92, 0x510000
	s_addc_u32 s5, s93, 0
	v_mov_b32_e32 v27, 1
	s_bfe_u32 s8, s2, 0x30003
	s_lshl_b32 s8, s8, 2
	s_add_u32 s8, s8, s3
	s_add_u32 s8, s8, 0xc0
	v_mov_b32_e32 v26, s8
	global_atomic_add v26, v27, s[4:5]
	s_bfe_u32 s8, s2, 0x30003
	s_lshl_b32 s8, s8, 2
	s_add_u32 s8, s8, s3
	s_add_u32 s8, s8, 0xc0
	v_mov_b32_e32 v26, s8
	v_mov_b32_e32 v25, 8
	s_mov_b32 s8, 0
	s_branch .Lfb_spin_3

.LBB0_949:
	s_waitcnt vmcnt(0)
	v_readfirstlane_b32 s0, v194
	s_cmp_gt_u32 s0, 63
	s_waitcnt vmcnt(0)
	s_barrier
	s_cbranch_scc1 .LBB0_1003
	v_mbcnt_lo_u32_b32 v0, -1, 0
	v_mbcnt_hi_u32_b32 v0, -1, v0
	s_nop 0
	v_cmp_eq_u32_e32 vcc, 0, v0
	s_and_saveexec_b64 s[0:1], vcc
	s_cbranch_execz .LBB0_1002
	v_mov_b32_e32 v20, 0x23ff0
	s_waitcnt vmcnt(0) lgkmcnt(0)
	ds_read_b128 v[20:23], v20
	s_waitcnt lgkmcnt(0)
	v_readfirstlane_b32 s3, v22
	s_nop 0
	s_cmp_eq_u32 s3, 0
	s_cbranch_scc1 .Lfb_slow_5
	v_readfirstlane_b32 s8, v20
	s_cmp_eq_u32 s8, 32
	s_cbranch_scc0 .Lfb_xcd_5
	buffer_inv sc1
	s_getreg_b32 s3, hwreg(HW_REG_XCC_ID, 0, 4)
	s_and_b32 s3, s3, 7
	s_lshl_b32 s3, s3, 8
	s_add_u32 s3, s3, 0x3600
	s_add_u32 s4, s92, 0x510000
	s_addc_u32 s5, s93, 0
	v_mov_b32_e32 v27, 1
	s_bfe_u32 s8, s2, 0x20006
	s_lshl_b32 s8, s8, 2
	s_add_u32 s8, s8, s3
	s_add_u32 s8, s8, 0xe0
	v_mov_b32_e32 v26, s8
	global_atomic_add v26, v27, s[4:5]
	s_bfe_u32 s8, s2, 0x20006
	s_lshl_b32 s8, s8, 2
	s_add_u32 s8, s8, s3
	s_add_u32 s8, s8, 0xe0
	v_mov_b32_e32 v26, s8
	v_mov_b32_e32 v25, 24
	s_mov_b32 s8, 0
	s_branch .Lfb_spin_5

.LBB0_1157:
	s_waitcnt vmcnt(0)
	v_readfirstlane_b32 s0, v194
	v_readlane_b32 s62, v241, 5
	s_cmp_gt_u32 s0, 63
	v_readlane_b32 s63, v241, 6
	s_waitcnt lgkmcnt(0)
	s_barrier
	s_cbranch_scc1 .LBB0_1211
	v_mbcnt_lo_u32_b32 v0, -1, 0
	v_mbcnt_hi_u32_b32 v0, -1, v0
	s_nop 0
	v_cmp_eq_u32_e32 vcc, 0, v0
	s_and_saveexec_b64 s[0:1], vcc
	s_cbranch_execz .LBB0_1210
	v_mov_b32_e32 v20, 0x23ff0
	s_waitcnt vmcnt(0) lgkmcnt(0)
	ds_read_b128 v[20:23], v20
	s_waitcnt lgkmcnt(0)
	v_readfirstlane_b32 s3, v22
	s_nop 0
	s_cmp_eq_u32 s3, 0
	s_cbranch_scc1 .Lfb_slow_6
	v_readfirstlane_b32 s8, v20
	s_cmp_eq_u32 s8, 32
	s_cbranch_scc0 .Lfb_xcd_6
	buffer_inv sc1
	s_getreg_b32 s3, hwreg(HW_REG_XCC_ID, 0, 4)
	s_and_b32 s3, s3, 7
	s_lshl_b32 s3, s3, 8
	s_add_u32 s3, s3, 0x3600
	s_add_u32 s4, s92, 0x510000
	s_addc_u32 s5, s93, 0
	v_mov_b32_e32 v27, 1
	s_bfe_u32 s8, s2, 0x20003
	s_lshl_b32 s8, s8, 2
	s_add_u32 s8, s8, s3
	s_add_u32 s8, s8, 0x40
	v_mov_b32_e32 v26, s8
	global_atomic_add v26, v27, s[4:5]
	s_mov_b32 s8, s3
	s_add_u32 s8, s8, 0x50
	v_mov_b32_e32 v26, s8
	global_atomic_add v26, v27, s[4:5]
	s_bfe_u32 s8, s2, 0x30003
	s_bitcmp1_b32 s2, 5
	s_cbranch_scc0 .Lfb_aw_6
	s_xor_b32 s8, s8, 7
.Lfb_aw_6:
	s_lshl_b32 s8, s8, 2
	s_add_u32 s8, s8, s3
	s_add_u32 s8, s8, 0x40
	v_mov_b32_e32 v26, s8
	v_mov_b32_e32 v25, 8
	s_mov_b32 s8, 0
	s_branch .Lfb_spin_6

.LBB0_1249:
	s_waitcnt vmcnt(0)
	v_readfirstlane_b32 s3, v194
	s_cmp_gt_u32 s3, 63
	s_waitcnt lgkmcnt(0)
	s_barrier
	s_cbranch_scc1 .LBB0_1303
	v_mbcnt_lo_u32_b32 v0, -1, 0
	v_mbcnt_hi_u32_b32 v0, -1, v0
	s_nop 0
	v_cmp_eq_u32_e32 vcc, 0, v0
	s_and_saveexec_b64 s[6:7], vcc
	s_cbranch_execz .LBB0_1302
	v_mov_b32_e32 v20, 0x23ff0
	s_waitcnt vmcnt(0) lgkmcnt(0)
	ds_read_b128 v[20:23], v20
	s_waitcnt lgkmcnt(0)
	v_readfirstlane_b32 s3, v22
	s_nop 0
	s_cmp_eq_u32 s3, 0
	s_cbranch_scc1 .Lfb_slow_7
	v_readfirstlane_b32 s8, v20
	s_cmp_eq_u32 s8, 32
	s_cbranch_scc0 .Lfb_xcd_7
	buffer_inv sc1
	s_getreg_b32 s3, hwreg(HW_REG_XCC_ID, 0, 4)
	s_and_b32 s3, s3, 7
	s_lshl_b32 s3, s3, 8
	s_add_u32 s3, s3, 0x3600
	s_add_u32 s4, s92, 0x510000
	s_addc_u32 s5, s93, 0
	v_mov_b32_e32 v27, 1
	s_bfe_u32 s8, s2, 0x30003
	s_lshl_b32 s8, s8, 2
	s_add_u32 s8, s8, s3
	s_add_u32 s8, s8, 0xc0
	v_mov_b32_e32 v26, s8
	global_atomic_add v26, v27, s[4:5]
	s_mov_b32 s8, s3
	s_add_u32 s8, s8, 0x54
	v_mov_b32_e32 v26, s8
	global_atomic_add v26, v27, s[4:5]
	s_bfe_u32 s8, s2, 0x30003
	s_lshl_b32 s8, s8, 2
	s_add_u32 s8, s8, s3
	s_add_u32 s8, s8, 0xc0
	v_mov_b32_e32 v26, s8
	v_mov_b32_e32 v25, 12
	s_mov_b32 s8, 0

.Lfb_gd_7_0:
	s_mov_b32 s8, s3
	s_add_u32 s8, s8, 0x50
	v_mov_b32_e32 v26, s8
	v_mov_b32_e32 v25, 32
	s_mov_b32 s8, 0
	s_branch .Lfb_spin_7

.LBB0_1332:
	s_waitcnt vmcnt(0)
	v_readfirstlane_b32 s0, v194
	s_cmp_gt_u32 s0, 63
	s_waitcnt vmcnt(0)
	s_barrier
	s_cbranch_scc1 .LBB0_1386
	v_mbcnt_lo_u32_b32 v0, -1, 0
	v_mbcnt_hi_u32_b32 v0, -1, v0
	s_nop 0
	v_cmp_eq_u32_e32 vcc, 0, v0
	s_and_saveexec_b64 s[0:1], vcc
	s_cbranch_execz .LBB0_1385
	v_mov_b32_e32 v20, 0x23ff0
	s_waitcnt vmcnt(0) lgkmcnt(0)
	ds_read_b128 v[20:23], v20
	s_waitcnt lgkmcnt(0)
	v_readfirstlane_b32 s3, v22
	s_nop 0
	s_cmp_eq_u32 s3, 0
	s_cbranch_scc1 .Lfb_slow_8
	v_readfirstlane_b32 s8, v20
	s_cmp_eq_u32 s8, 32
	s_cbranch_scc0 .Lfb_xcd_8
	buffer_inv sc1
	s_getreg_b32 s3, hwreg(HW_REG_XCC_ID, 0, 4)
	s_and_b32 s3, s3, 7
	s_lshl_b32 s3, s3, 8
	s_add_u32 s3, s3, 0x3600
	s_add_u32 s4, s92, 0x510000
	s_addc_u32 s5, s93, 0
	v_mov_b32_e32 v27, 1
	s_bfe_u32 s8, s2, 0x30003
	s_lshl_b32 s8, s8, 2
	s_add_u32 s8, s8, s3
	s_add_u32 s8, s8, 0xc0
	v_mov_b32_e32 v26, s8
	global_atomic_add v26, v27, s[4:5]
	s_bfe_u32 s8, s2, 0x30003
	s_lshl_b32 s8, s8, 2
	s_add_u32 s8, s8, s3
	s_add_u32 s8, s8, 0xc0
	v_mov_b32_e32 v26, s8
	v_mov_b32_e32 v25, 16
	s_mov_b32 s8, 0

.Lfb_gd_8_0:
	s_mov_b32 s8, s3
	s_add_u32 s8, s8, 0x54
	v_mov_b32_e32 v26, s8
	v_mov_b32_e32 v25, 32
	s_mov_b32 s8, 0
	s_branch .Lfb_spin_8
